# SGU: WG handles the 4 heads of one (b,chunk) consecutively (guarded G==256) and reuses LayerNorm sum/rstd for heads 1-3 (skips redundant stats recompute)
# speedup vs baseline: 1.0155x; 1.0155x over previous
.LBB0_823:
	s_or_b64 exec, exec, s[0:1]
	v_readlane_b32 s0, v254, 31
	v_readlane_b32 s1, v254, 32
	s_andn2_b64 vcc, exec, s[0:1]
	s_movk_i32 s35, 0x3000
	v_cndmask_b32_e64 v0, 0, 1, s[0:1]
	v_cmp_ne_u32_e64 s[38:39], 1, v0
	s_cbranch_vccnz .LBB0_826
	s_lshl_b64 s[0:1], s[86:87], 17
	v_readlane_b32 s3, v253, 10
	s_mov_b64 s[8:9], s[86:87]
	s_add_u32 s3, s3, s0
	v_readlane_b32 s0, v253, 11
	s_addc_u32 s11, s0, s1
	s_lshl_b32 s92, s8, 9
	v_readlane_b32 s64, v252, 27
	s_lshl_b64 s[0:1], s[92:93], 2
	v_readlane_b32 s74, v252, 37
	v_readlane_b32 s68, v252, 31
	v_readlane_b32 s69, v252, 32
	v_readlane_b32 s75, v252, 38
	s_add_u32 s12, s74, s0
	v_readlane_b32 s76, v252, 39
	v_readlane_b32 s68, v252, 4
	s_addc_u32 s16, s75, s1
	v_readlane_b32 s65, v252, 28
	v_readlane_b32 s66, v252, 29
	v_readlane_b32 s67, v252, 30
	v_readlane_b32 s70, v252, 33
	v_readlane_b32 s71, v252, 34
	v_readlane_b32 s72, v252, 35
	v_readlane_b32 s73, v252, 36
	v_readlane_b32 s77, v252, 40
	v_readlane_b32 s78, v252, 41
	v_readlane_b32 s79, v252, 42
	v_readlane_b32 s69, v252, 5
	s_add_u32 s17, s76, s0
	s_mov_b32 s94, s68
	s_addc_u32 s18, s77, s1
	v_readlane_b32 s64, v252, 52
	v_readlane_b32 s7, v255, 52
	v_readlane_b32 s65, v252, 53
	v_readlane_b32 s66, v252, 54
	v_readlane_b32 s67, v252, 55
	v_readlane_b32 s68, v252, 56
	v_readlane_b32 s69, v252, 57
	v_readlane_b32 s70, v252, 58
	s_add_u32 s0, s64, s0
	v_readlane_b32 s8, v252, 0
	v_readlane_b32 s59, v252, 47
	v_readlane_b32 s58, v252, 46
	v_readlane_b32 s57, v252, 45
	v_readlane_b32 s56, v253, 7
	s_mov_b64 s[66:67], 0x1400
	v_readlane_b32 s34, v254, 35
	v_readlane_b32 s33, v254, 34
	v_readlane_b32 s10, v254, 33
	v_readlane_b32 s69, v255, 54
	v_readlane_b32 s68, v255, 53
	s_mov_b32 s70, s7
	s_addc_u32 s1, s65, s1
	v_readlane_b32 s64, v255, 44
	s_mov_b32 s65, s8
	v_readlane_b32 s71, v252, 59
	v_readlane_b32 s72, v252, 60
	v_readlane_b32 s73, v252, 61
	v_readlane_b32 s74, v252, 62
	v_readlane_b32 s75, v252, 63
	v_readlane_b32 s76, v253, 0
	v_readlane_b32 s77, v253, 1
	v_readlane_b32 s78, v253, 2
	v_readlane_b32 s79, v253, 3
	v_readlane_b32 s9, v252, 1
	s_mov_b32 s98, s94
	s_mov_b32 s99, s68
	s_movk_i32 s88, 0x3ff
	s_cmpk_lg_i32 s94, 0x100
	s_cbranch_scc1 .Lsgu_map_done
	s_lshl_b32 s65, s65, 2
	s_lshl_b32 s64, s65, 5
	s_mov_b32 s98, 1
	s_mov_b32 s99, 32
	s_add_i32 s88, s65, 3
.Lsgu_map_done:
.LBB0_825:
	s_and_b32 s45, s65, 3
	s_cmp_lg_u32 s98, 1
	s_cbranch_scc1 .Lsgu_full
	s_cmp_lg_u32 s45, 0
	s_cbranch_scc1 .Lsgu_fast
.Lsgu_full:
	s_ashr_i32 s8, s65, 7
	v_mov_b32_e32 v130, v217
	s_ashr_i32 s9, s8, 31
	v_ashrrev_i32_e32 v0, 2, v130
	s_lshl_b64 s[36:37], s[8:9], 12
	s_and_b32 s7, s64, 0xf80
	v_add_u32_e32 v44, s10, v0
	s_or_b32 s36, s36, s7
	v_ashrrev_i32_e32 v45, 31, v44
	v_lshl_add_u64 v[0:1], s[36:37], 0, v[44:45]
	v_mov_b64_e32 v[2:3], s[82:83]
	v_mad_u64_u32 v[2:3], s[8:9], v0, s14, v[2:3]
	v_lshlrev_b32_e32 v0, 3, v130
	v_and_b32_e32 v45, 24, v0
	v_mad_i32_i24 v3, v1, s14, v3
	v_lshlrev_b32_e32 v194, 1, v45
	v_lshl_add_u64 v[0:1], v[2:3], 0, v[194:195]
	v_lshl_add_u64 v[2:3], v[0:1], 0, s[66:67]
	v_add_co_u32_e32 v0, vcc, s15, v0
	v_mov_b32_e32 v100, v195
	s_nop 0
	v_addc_co_u32_e32 v1, vcc, 0, v1, vcc
	global_load_dwordx4 v[46:49], v[0:1], off offset:1024
	global_load_dwordx4 v[50:53], v[2:3], off offset:64
	global_load_dwordx4 v[54:57], v[2:3], off offset:128
	global_load_dwordx4 v[60:63], v[2:3], off offset:192
	global_load_dwordx4 v[68:71], v[2:3], off offset:256
	global_load_dwordx4 v[72:75], v[2:3], off offset:320
	global_load_dwordx4 v[76:79], v[2:3], off offset:384
	global_load_dwordx4 v[80:83], v[2:3], off offset:448
	global_load_dwordx4 v[110:113], v[2:3], off offset:512
	global_load_dwordx4 v[40:43], v[2:3], off offset:576
	global_load_dwordx4 v[36:39], v[2:3], off offset:640
	global_load_dwordx4 v[32:35], v[2:3], off offset:704
	global_load_dwordx4 v[28:31], v[2:3], off offset:768
	global_load_dwordx4 v[24:27], v[2:3], off offset:832
	global_load_dwordx4 v[20:23], v[2:3], off offset:896
	global_load_dwordx4 v[16:19], v[2:3], off offset:960
	s_and_b32 s45, s65, 3
	s_lshl_b32 s60, s45, 7
	s_lshl_b32 s92, s45, 8
	s_lshl_b32 s7, s45, 9
	s_add_u32 s40, s12, s7
	s_addc_u32 s41, s16, 0
	v_lshl_add_u64 v[0:1], v[2:3], 0, s[92:93]
	s_add_u32 s46, s17, s7
	global_load_dwordx4 v[12:15], v[0:1], off
	global_load_dwordx4 v[8:11], v[0:1], off offset:64
	global_load_dwordx4 v[4:7], v[0:1], off offset:128
	s_nop 0
	global_load_dwordx4 v[0:3], v[0:1], off offset:192
	s_addc_u32 s47, s18, 0
	s_add_u32 s8, s33, s92
	v_and_b32_e32 v132, 15, v130
	s_addc_u32 s9, s34, 0
	s_lshl_b32 s7, s45, 15
	v_lshlrev_b32_e32 v194, 8, v132
	s_waitcnt vmcnt(19)
	v_lshlrev_b32_e32 v115, 16, v48
	v_lshlrev_b32_e32 v114, 16, v46
	v_and_b32_e32 v117, 0xffff0000, v48
	v_and_b32_e32 v116, 0xffff0000, v46
	v_lshlrev_b32_e32 v119, 16, v49
	v_lshlrev_b32_e32 v118, 16, v47
	v_and_b32_e32 v121, 0xffff0000, v49
	v_and_b32_e32 v120, 0xffff0000, v47
	v_pk_add_f32 v[58:59], v[114:115], v[116:117]
	v_pk_add_f32 v[46:47], v[118:119], v[120:121]
	s_waitcnt vmcnt(18)
	v_lshlrev_b32_e32 v109, 16, v51
	v_lshlrev_b32_e32 v108, 16, v50
	v_and_b32_e32 v107, 0xffff0000, v51
	v_and_b32_e32 v106, 0xffff0000, v50
	v_lshlrev_b32_e32 v105, 16, v53
	v_lshlrev_b32_e32 v104, 16, v52
	v_and_b32_e32 v103, 0xffff0000, v53
	v_and_b32_e32 v102, 0xffff0000, v52
	v_pk_add_f32 v[46:47], v[58:59], v[46:47]
	v_pk_add_f32 v[48:49], v[108:109], v[106:107]
	v_pk_add_f32 v[50:51], v[104:105], v[102:103]
	s_waitcnt vmcnt(16)
	v_lshlrev_b32_e32 v142, 16, v60
	v_lshlrev_b32_e32 v143, 16, v61
	v_and_b32_e32 v144, 0xffff0000, v61
	v_pk_add_f32 v[46:47], v[46:47], v[46:47] op_sel:[0,1] op_sel_hi:[1,0]
	v_pk_add_f32 v[48:49], v[48:49], v[48:49] op_sel:[0,1] op_sel_hi:[1,0]
	v_pk_add_f32 v[50:51], v[50:51], v[50:51] op_sel:[0,1] op_sel_hi:[1,0]
	v_lshlrev_b32_e32 v131, 16, v54
	v_and_b32_e32 v133, 0xffff0000, v54
	v_lshlrev_b32_e32 v136, 16, v55
	v_and_b32_e32 v137, 0xffff0000, v55
	v_lshlrev_b32_e32 v138, 16, v56
	v_and_b32_e32 v139, 0xffff0000, v56
	v_lshlrev_b32_e32 v140, 16, v57
	v_and_b32_e32 v141, 0xffff0000, v57
	v_and_b32_e32 v101, 0xffff0000, v60
	v_mov_b32_e32 v47, v142
	v_mov_b32_e32 v49, v143
	v_mov_b32_e32 v51, v144
	v_add_f32_e32 v54, v131, v133
	v_add_f32_e32 v58, v136, v137
	v_add_f32_e32 v64, v138, v139
	v_add_f32_e32 v66, v140, v141
	v_lshlrev_b32_e32 v55, 16, v62
	v_and_b32_e32 v59, 0xffff0000, v62
	v_lshlrev_b32_e32 v65, 16, v63
	v_and_b32_e32 v67, 0xffff0000, v63
	v_pk_add_f32 v[46:47], v[46:47], v[100:101]
	v_pk_add_f32 v[48:49], v[48:49], v[50:51]
	v_pk_add_f32 v[50:51], v[64:65], v[66:67]
	v_pk_add_f32 v[46:47], v[46:47], v[48:49]
	v_pk_add_f32 v[48:49], v[54:55], v[58:59]
	s_waitcnt vmcnt(15)
	v_lshlrev_b32_e32 v95, 16, v70
	v_pk_add_f32 v[48:49], v[48:49], v[50:51]
	v_lshlrev_b32_e32 v94, 16, v68
	v_and_b32_e32 v93, 0xffff0000, v70
	v_and_b32_e32 v92, 0xffff0000, v68
	v_lshlrev_b32_e32 v99, 16, v71
	v_lshlrev_b32_e32 v98, 16, v69
	v_and_b32_e32 v97, 0xffff0000, v71
	v_and_b32_e32 v96, 0xffff0000, v69
	v_pk_add_f32 v[56:57], v[46:47], v[48:49]
	v_pk_add_f32 v[46:47], v[94:95], v[92:93]
	v_pk_add_f32 v[48:49], v[98:99], v[96:97]
	s_waitcnt vmcnt(14)
	v_lshlrev_b32_e32 v91, 16, v73
	v_pk_add_f32 v[60:61], v[46:47], v[48:49]
	v_lshlrev_b32_e32 v90, 16, v72
	v_and_b32_e32 v89, 0xffff0000, v73
	v_and_b32_e32 v88, 0xffff0000, v72
	v_lshlrev_b32_e32 v87, 16, v75
	v_lshlrev_b32_e32 v86, 16, v74
	v_and_b32_e32 v85, 0xffff0000, v75
	v_and_b32_e32 v84, 0xffff0000, v74
	s_waitcnt vmcnt(12)
	v_lshlrev_b32_e32 v148, 16, v80
	v_and_b32_e32 v149, 0xffff0000, v80
	v_pk_add_f32 v[56:57], v[56:57], v[56:57] op_sel:[0,1] op_sel_hi:[1,0]
	v_pk_add_f32 v[60:61], v[60:61], v[60:61] op_sel:[0,1] op_sel_hi:[1,0]
	v_pk_add_f32 v[62:63], v[90:91], v[88:89]
	v_pk_add_f32 v[68:69], v[86:87], v[84:85]
	v_mov_b32_e32 v57, v148
	v_mov_b32_e32 v61, v149
	v_lshlrev_b32_e32 v150, 16, v81
	v_and_b32_e32 v151, 0xffff0000, v81
	v_pk_add_f32 v[56:57], v[56:57], v[60:61]
	v_pk_add_f32 v[60:61], v[62:63], v[62:63] op_sel:[0,1] op_sel_hi:[1,0]
	v_pk_add_f32 v[62:63], v[68:69], v[68:69] op_sel:[0,1] op_sel_hi:[1,0]
	v_lshlrev_b32_e32 v54, 16, v76
	v_and_b32_e32 v58, 0xffff0000, v76
	v_lshlrev_b32_e32 v64, 16, v77
	v_and_b32_e32 v66, 0xffff0000, v77
	v_lshlrev_b32_e32 v100, 16, v78
	v_and_b32_e32 v145, 0xffff0000, v78
	v_lshlrev_b32_e32 v146, 16, v79
	v_and_b32_e32 v147, 0xffff0000, v79
	v_mov_b32_e32 v61, v150
	v_mov_b32_e32 v63, v151
	v_add_f32_e32 v46, v54, v58
	v_add_f32_e32 v48, v64, v66
	v_add_f32_e32 v50, v100, v145
	v_add_f32_e32 v52, v146, v147
	v_lshlrev_b32_e32 v47, 16, v82
	v_and_b32_e32 v49, 0xffff0000, v82
	v_lshlrev_b32_e32 v51, 16, v83
	v_and_b32_e32 v53, 0xffff0000, v83
	v_pk_add_f32 v[60:61], v[60:61], v[62:63]
	v_pk_add_f32 v[62:63], v[50:51], v[52:53]
	v_pk_add_f32 v[56:57], v[56:57], v[60:61]
	v_pk_add_f32 v[60:61], v[46:47], v[48:49]
	s_waitcnt vmcnt(11)
	v_lshlrev_b32_e32 v79, 16, v112
	v_pk_add_f32 v[60:61], v[60:61], v[62:63]
	v_lshlrev_b32_e32 v78, 16, v110
	v_and_b32_e32 v77, 0xffff0000, v112
	v_and_b32_e32 v76, 0xffff0000, v110
	v_lshlrev_b32_e32 v83, 16, v113
	v_lshlrev_b32_e32 v82, 16, v111
	v_and_b32_e32 v81, 0xffff0000, v113
	v_and_b32_e32 v80, 0xffff0000, v111
	v_pk_add_f32 v[56:57], v[56:57], v[60:61]
	v_pk_add_f32 v[60:61], v[78:79], v[76:77]
	v_pk_add_f32 v[62:63], v[82:83], v[80:81]
	s_waitcnt vmcnt(10)
	v_lshlrev_b32_e32 v75, 16, v41
	v_pk_add_f32 v[60:61], v[60:61], v[62:63]
	v_lshlrev_b32_e32 v74, 16, v40
	v_and_b32_e32 v73, 0xffff0000, v41
	v_and_b32_e32 v72, 0xffff0000, v40
	v_lshlrev_b32_e32 v71, 16, v43
	v_lshlrev_b32_e32 v70, 16, v42
	v_and_b32_e32 v69, 0xffff0000, v43
	v_and_b32_e32 v68, 0xffff0000, v42
	s_waitcnt vmcnt(9)
	v_lshlrev_b32_e32 v50, 16, v37
	v_and_b32_e32 v52, 0xffff0000, v37
	v_lshlrev_b32_e32 v154, 16, v39
	v_and_b32_e32 v155, 0xffff0000, v39
	s_waitcnt vmcnt(8)
	v_lshlrev_b32_e32 v156, 16, v32
	v_and_b32_e32 v157, 0xffff0000, v32
	v_lshlrev_b32_e32 v158, 16, v33
	v_and_b32_e32 v159, 0xffff0000, v33
	v_lshlrev_b32_e32 v37, 16, v34
	v_and_b32_e32 v41, 0xffff0000, v34
	v_lshlrev_b32_e32 v39, 16, v35
	v_and_b32_e32 v43, 0xffff0000, v35
	v_pk_add_f32 v[32:33], v[56:57], v[56:57] op_sel:[0,1] op_sel_hi:[1,0]
	v_pk_add_f32 v[34:35], v[60:61], v[60:61] op_sel:[0,1] op_sel_hi:[1,0]
	v_pk_add_f32 v[62:63], v[74:75], v[72:73]
	v_pk_add_f32 v[110:111], v[70:71], v[68:69]
	v_mov_b32_e32 v33, v156
	v_mov_b32_e32 v35, v157
	v_pk_add_f32 v[32:33], v[32:33], v[34:35]
	v_pk_add_f32 v[34:35], v[62:63], v[62:63] op_sel:[0,1] op_sel_hi:[1,0]
	v_pk_add_f32 v[56:57], v[110:111], v[110:111] op_sel:[0,1] op_sel_hi:[1,0]
	v_lshlrev_b32_e32 v46, 16, v36
	v_and_b32_e32 v48, 0xffff0000, v36
	v_lshlrev_b32_e32 v152, 16, v38
	v_and_b32_e32 v153, 0xffff0000, v38
	v_mov_b32_e32 v35, v158
	v_mov_b32_e32 v57, v159
	v_add_f32_e32 v36, v46, v48
	v_add_f32_e32 v40, v50, v52
	v_add_f32_e32 v38, v152, v153
	v_add_f32_e32 v42, v154, v155
	v_pk_add_f32 v[34:35], v[34:35], v[56:57]
	v_pk_add_f32 v[56:57], v[38:39], v[42:43]
	v_pk_add_f32 v[32:33], v[32:33], v[34:35]
	v_pk_add_f32 v[34:35], v[36:37], v[40:41]
	s_waitcnt vmcnt(5)
	v_lshlrev_b32_e32 v40, 16, v21
	v_pk_add_f32 v[34:35], v[34:35], v[56:57]
	v_and_b32_e32 v42, 0xffff0000, v21
	v_pk_add_f32 v[32:33], v[32:33], v[34:35]
	v_and_b32_e32 v21, 64, v224
	v_pk_add_f32 v[110:111], v[32:33], v[32:33] op_sel:[0,1] op_sel_hi:[1,0]
	v_lshlrev_b32_e32 v57, 16, v30
	v_lshlrev_b32_e32 v56, 16, v28
	v_and_b32_e32 v33, 0xffff0000, v30
	v_and_b32_e32 v32, 0xffff0000, v28
	v_lshlrev_b32_e32 v63, 16, v31
	v_lshlrev_b32_e32 v62, 16, v29
	v_and_b32_e32 v61, 0xffff0000, v31
	v_and_b32_e32 v60, 0xffff0000, v29
	v_lshlrev_b32_e32 v36, 16, v20
	v_and_b32_e32 v38, 0xffff0000, v20
	v_xor_b32_e32 v20, 1, v224
	v_add_u32_e32 v21, 64, v21
	v_pk_add_f32 v[34:35], v[56:57], v[32:33]
	v_pk_add_f32 v[28:29], v[62:63], v[60:61]
	v_cmp_lt_i32_e32 vcc, v20, v21
	v_pk_add_f32 v[28:29], v[34:35], v[28:29]
	v_lshlrev_b32_e32 v35, 16, v25
	v_lshlrev_b32_e32 v34, 16, v24
	v_and_b32_e32 v31, 0xffff0000, v25
	v_and_b32_e32 v30, 0xffff0000, v24
	v_cndmask_b32_e32 v20, v224, v20, vcc
	v_pk_add_f32 v[24:25], v[34:35], v[30:31]
	v_lshlrev_b32_e32 v164, 2, v20
	v_xor_b32_e32 v20, 2, v224
	v_pk_add_f32 v[112:113], v[28:29], v[28:29] op_sel:[0,1] op_sel_hi:[1,0]
	v_pk_add_f32 v[122:123], v[24:25], v[24:25] op_sel:[0,1] op_sel_hi:[1,0]
	v_lshlrev_b32_e32 v29, 16, v27
	v_lshlrev_b32_e32 v28, 16, v26
	v_and_b32_e32 v25, 0xffff0000, v27
	v_and_b32_e32 v24, 0xffff0000, v26
	v_cmp_lt_i32_e32 vcc, v20, v21
	v_pk_add_f32 v[26:27], v[28:29], v[24:25]
	v_lshlrev_b32_e32 v160, 16, v22
	v_cndmask_b32_e32 v20, v224, v20, vcc
	v_pk_add_f32 v[26:27], v[26:27], v[26:27] op_sel:[0,1] op_sel_hi:[1,0]
	v_and_b32_e32 v161, 0xffff0000, v22
	v_lshlrev_b32_e32 v162, 16, v23
	v_and_b32_e32 v163, 0xffff0000, v23
	v_lshlrev_b32_e32 v165, 2, v20
	s_waitcnt vmcnt(4)
	v_and_b32_e32 v20, 0xffff0000, v19
	v_lshlrev_b32_e32 v21, 16, v19
	v_and_b32_e32 v22, 0xffff0000, v18
	v_lshlrev_b32_e32 v23, 16, v18
	v_and_b32_e32 v18, 0xffff0000, v17
	v_lshlrev_b32_e32 v19, 16, v17
	v_mov_b32_e32 v123, v19
	v_mov_b32_e32 v27, v18
	v_pk_add_f32 v[122:123], v[122:123], v[26:27]
	v_and_b32_e32 v26, 0xffff0000, v16
	v_lshlrev_b32_e32 v27, 16, v16
	v_add_f32_e32 v124, v36, v38
	v_add_f32_e32 v126, v40, v42
	v_add_f32_e32 v128, v160, v161
	v_add_f32_e32 v134, v162, v163
	v_mov_b32_e32 v129, v21
	v_mov_b32_e32 v135, v20
	v_mov_b32_e32 v125, v23
	v_mov_b32_e32 v127, v22
	v_mov_b32_e32 v111, v27
	v_mov_b32_e32 v113, v26
	v_pk_add_f32 v[128:129], v[128:129], v[134:135]
	v_pk_add_f32 v[124:125], v[124:125], v[126:127]
	v_pk_add_f32 v[16:17], v[110:111], v[112:113]
	v_pk_add_f32 v[124:125], v[124:125], v[128:129]
	v_pk_add_f32 v[16:17], v[16:17], v[122:123]
	s_nop 0
	v_pk_add_f32 v[16:17], v[16:17], v[124:125]
	s_nop 0
	v_add_f32_e32 v16, v16, v17
	ds_bpermute_b32 v17, v164, v16
	s_waitcnt lgkmcnt(0)
	v_add_f32_e32 v16, v16, v17
	ds_bpermute_b32 v17, v165, v16
	s_waitcnt lgkmcnt(0)
	v_add_f32_e32 v17, v16, v17
	v_fmac_f32_e32 v114, 0xbb000000, v17
	v_mul_f32_e32 v110, v114, v114
	v_fmac_f32_e32 v116, 0xbb000000, v17
	v_fmac_f32_e32 v110, v116, v116
	v_fmac_f32_e32 v118, 0xbb000000, v17
	v_fmac_f32_e32 v110, v118, v118
	v_fmac_f32_e32 v120, 0xbb000000, v17
	v_fmac_f32_e32 v110, v120, v120
	v_fmac_f32_e32 v115, 0xbb000000, v17
	v_fmac_f32_e32 v110, v115, v115
	v_fmac_f32_e32 v117, 0xbb000000, v17
	v_fmac_f32_e32 v110, v117, v117
	v_fmac_f32_e32 v119, 0xbb000000, v17
	v_fmac_f32_e32 v110, v119, v119
	v_fmac_f32_e32 v121, 0xbb000000, v17
	v_fmac_f32_e32 v110, v121, v121
	v_fmac_f32_e32 v108, 0xbb000000, v17
	v_fmac_f32_e32 v110, v108, v108
	v_fmac_f32_e32 v106, 0xbb000000, v17
	v_fmac_f32_e32 v110, v106, v106
	v_fmac_f32_e32 v109, 0xbb000000, v17
	v_fmac_f32_e32 v110, v109, v109
	v_fmac_f32_e32 v107, 0xbb000000, v17
	v_fmac_f32_e32 v110, v107, v107
	v_fmac_f32_e32 v104, 0xbb000000, v17
	v_fmac_f32_e32 v110, v104, v104
	v_fmac_f32_e32 v102, 0xbb000000, v17
	v_fmac_f32_e32 v110, v102, v102
	v_fmac_f32_e32 v105, 0xbb000000, v17
	v_fmac_f32_e32 v110, v105, v105
	v_fmac_f32_e32 v103, 0xbb000000, v17
	v_fmac_f32_e32 v110, v103, v103
	v_fmac_f32_e32 v131, 0xbb000000, v17
	v_fmac_f32_e32 v110, v131, v131
	v_fmac_f32_e32 v133, 0xbb000000, v17
	v_fmac_f32_e32 v110, v133, v133
	v_fmac_f32_e32 v136, 0xbb000000, v17
	v_fmac_f32_e32 v110, v136, v136
	v_fmac_f32_e32 v137, 0xbb000000, v17
	v_fmac_f32_e32 v110, v137, v137
	v_fmac_f32_e32 v138, 0xbb000000, v17
	v_fmac_f32_e32 v110, v138, v138
	v_fmac_f32_e32 v139, 0xbb000000, v17
	v_fmac_f32_e32 v110, v139, v139
	v_fmac_f32_e32 v140, 0xbb000000, v17
	v_fmac_f32_e32 v110, v140, v140
	v_fmac_f32_e32 v141, 0xbb000000, v17
	v_fmac_f32_e32 v110, v141, v141
	v_fmac_f32_e32 v142, 0xbb000000, v17
	v_fmac_f32_e32 v110, v142, v142
	v_fmac_f32_e32 v101, 0xbb000000, v17
	v_fmac_f32_e32 v110, v101, v101
	v_fmac_f32_e32 v143, 0xbb000000, v17
	v_fmac_f32_e32 v110, v143, v143
	v_fmac_f32_e32 v144, 0xbb000000, v17
	v_fmac_f32_e32 v110, v144, v144
	v_fmac_f32_e32 v55, 0xbb000000, v17
	v_fmac_f32_e32 v110, v55, v55
	v_fmac_f32_e32 v59, 0xbb000000, v17
	v_fmac_f32_e32 v110, v59, v59
	v_fmac_f32_e32 v65, 0xbb000000, v17
	v_fmac_f32_e32 v110, v65, v65
	v_fmac_f32_e32 v67, 0xbb000000, v17
	v_fmac_f32_e32 v110, v67, v67
	v_fmac_f32_e32 v94, 0xbb000000, v17
	v_fmac_f32_e32 v110, v94, v94
	v_fmac_f32_e32 v92, 0xbb000000, v17
	v_fmac_f32_e32 v110, v92, v92
	v_fmac_f32_e32 v98, 0xbb000000, v17
	v_fmac_f32_e32 v110, v98, v98
	v_fmac_f32_e32 v96, 0xbb000000, v17
	v_fmac_f32_e32 v110, v96, v96
	v_fmac_f32_e32 v95, 0xbb000000, v17
	v_fmac_f32_e32 v110, v95, v95
	v_fmac_f32_e32 v93, 0xbb000000, v17
	v_fmac_f32_e32 v110, v93, v93
	v_fmac_f32_e32 v99, 0xbb000000, v17
	v_fmac_f32_e32 v110, v99, v99
	v_fmac_f32_e32 v97, 0xbb000000, v17
	v_fmac_f32_e32 v110, v97, v97
	v_fmac_f32_e32 v90, 0xbb000000, v17
	v_fmac_f32_e32 v110, v90, v90
	v_fmac_f32_e32 v88, 0xbb000000, v17
	v_fmac_f32_e32 v110, v88, v88
	v_fmac_f32_e32 v91, 0xbb000000, v17
	v_fmac_f32_e32 v110, v91, v91
	v_fmac_f32_e32 v89, 0xbb000000, v17
	v_fmac_f32_e32 v110, v89, v89
	v_fmac_f32_e32 v86, 0xbb000000, v17
	v_fmac_f32_e32 v110, v86, v86
	v_fmac_f32_e32 v84, 0xbb000000, v17
	v_fmac_f32_e32 v110, v84, v84
	v_fmac_f32_e32 v87, 0xbb000000, v17
	v_fmac_f32_e32 v110, v87, v87
	v_fmac_f32_e32 v85, 0xbb000000, v17
	v_fmac_f32_e32 v110, v85, v85
	v_fmac_f32_e32 v54, 0xbb000000, v17
	v_fmac_f32_e32 v110, v54, v54
	v_fmac_f32_e32 v58, 0xbb000000, v17
	v_fmac_f32_e32 v110, v58, v58
	v_fmac_f32_e32 v64, 0xbb000000, v17
	v_fmac_f32_e32 v110, v64, v64
	v_fmac_f32_e32 v66, 0xbb000000, v17
	v_fmac_f32_e32 v110, v66, v66
	v_fmac_f32_e32 v100, 0xbb000000, v17
	v_fmac_f32_e32 v110, v100, v100
	v_fmac_f32_e32 v145, 0xbb000000, v17
	v_fmac_f32_e32 v110, v145, v145
	v_fmac_f32_e32 v146, 0xbb000000, v17
	v_fmac_f32_e32 v110, v146, v146
	v_fmac_f32_e32 v147, 0xbb000000, v17
	v_fmac_f32_e32 v110, v147, v147
	v_fmac_f32_e32 v148, 0xbb000000, v17
	v_fmac_f32_e32 v110, v148, v148
	v_fmac_f32_e32 v149, 0xbb000000, v17
	v_fmac_f32_e32 v110, v149, v149
	v_fmac_f32_e32 v150, 0xbb000000, v17
	v_fmac_f32_e32 v110, v150, v150
	v_fmac_f32_e32 v151, 0xbb000000, v17
	v_fmac_f32_e32 v110, v151, v151
	v_fmac_f32_e32 v47, 0xbb000000, v17
	v_fmac_f32_e32 v110, v47, v47
	v_fmac_f32_e32 v49, 0xbb000000, v17
	v_fmac_f32_e32 v110, v49, v49
	v_fmac_f32_e32 v51, 0xbb000000, v17
	v_fmac_f32_e32 v110, v51, v51
	v_fmac_f32_e32 v53, 0xbb000000, v17
	v_fmac_f32_e32 v110, v53, v53
	v_fmac_f32_e32 v78, 0xbb000000, v17
	v_fmac_f32_e32 v110, v78, v78
	v_fmac_f32_e32 v76, 0xbb000000, v17
	v_fmac_f32_e32 v110, v76, v76
	v_fmac_f32_e32 v82, 0xbb000000, v17
	v_fmac_f32_e32 v110, v82, v82
	v_fmac_f32_e32 v80, 0xbb000000, v17
	v_fmac_f32_e32 v110, v80, v80
	v_fmac_f32_e32 v79, 0xbb000000, v17
	v_fmac_f32_e32 v110, v79, v79
	v_fmac_f32_e32 v77, 0xbb000000, v17
	v_fmac_f32_e32 v110, v77, v77
	v_fmac_f32_e32 v83, 0xbb000000, v17
	v_fmac_f32_e32 v110, v83, v83
	v_fmac_f32_e32 v81, 0xbb000000, v17
	v_fmac_f32_e32 v110, v81, v81
	v_fmac_f32_e32 v74, 0xbb000000, v17
	v_fmac_f32_e32 v110, v74, v74
	v_fmac_f32_e32 v72, 0xbb000000, v17
	v_fmac_f32_e32 v110, v72, v72
	v_fmac_f32_e32 v75, 0xbb000000, v17
	v_fmac_f32_e32 v110, v75, v75
	v_fmac_f32_e32 v73, 0xbb000000, v17
	v_fmac_f32_e32 v110, v73, v73
	v_fmac_f32_e32 v70, 0xbb000000, v17
	v_fmac_f32_e32 v110, v70, v70
	v_fmac_f32_e32 v68, 0xbb000000, v17
	v_fmac_f32_e32 v110, v68, v68
	v_fmac_f32_e32 v71, 0xbb000000, v17
	v_fmac_f32_e32 v110, v71, v71
	v_fmac_f32_e32 v69, 0xbb000000, v17
	v_fmac_f32_e32 v110, v69, v69
	v_fmac_f32_e32 v46, 0xbb000000, v17
	v_fmac_f32_e32 v110, v46, v46
	v_fmac_f32_e32 v48, 0xbb000000, v17
	v_fmac_f32_e32 v110, v48, v48
	v_fmac_f32_e32 v50, 0xbb000000, v17
	v_fmac_f32_e32 v110, v50, v50
	v_fmac_f32_e32 v52, 0xbb000000, v17
	v_fmac_f32_e32 v110, v52, v52
	v_fmac_f32_e32 v152, 0xbb000000, v17
	v_fmac_f32_e32 v110, v152, v152
	v_fmac_f32_e32 v153, 0xbb000000, v17
	v_fmac_f32_e32 v110, v153, v153
	v_fmac_f32_e32 v154, 0xbb000000, v17
	v_fmac_f32_e32 v110, v154, v154
	v_fmac_f32_e32 v155, 0xbb000000, v17
	v_fmac_f32_e32 v110, v155, v155
	v_fmac_f32_e32 v156, 0xbb000000, v17
	v_fmac_f32_e32 v110, v156, v156
	v_fmac_f32_e32 v157, 0xbb000000, v17
	v_fmac_f32_e32 v110, v157, v157
	v_fmac_f32_e32 v158, 0xbb000000, v17
	v_fmac_f32_e32 v110, v158, v158
	v_fmac_f32_e32 v159, 0xbb000000, v17
	v_fmac_f32_e32 v110, v159, v159
	v_fmac_f32_e32 v37, 0xbb000000, v17
	v_fmac_f32_e32 v110, v37, v37
	v_fmac_f32_e32 v41, 0xbb000000, v17
	v_fmac_f32_e32 v110, v41, v41
	v_fmac_f32_e32 v39, 0xbb000000, v17
	v_fmac_f32_e32 v110, v39, v39
	v_fmac_f32_e32 v43, 0xbb000000, v17
	v_fmac_f32_e32 v110, v43, v43
	v_fmac_f32_e32 v56, 0xbb000000, v17
	v_fmac_f32_e32 v110, v56, v56
	v_fmac_f32_e32 v32, 0xbb000000, v17
	v_fmac_f32_e32 v110, v32, v32
	v_fmac_f32_e32 v62, 0xbb000000, v17
	v_fmac_f32_e32 v110, v62, v62
	v_fmac_f32_e32 v60, 0xbb000000, v17
	v_fmac_f32_e32 v110, v60, v60
	v_fmac_f32_e32 v57, 0xbb000000, v17
	v_fmac_f32_e32 v110, v57, v57
	v_fmac_f32_e32 v33, 0xbb000000, v17
	v_fmac_f32_e32 v110, v33, v33
	v_fmac_f32_e32 v63, 0xbb000000, v17
	v_fmac_f32_e32 v110, v63, v63
	v_fmac_f32_e32 v61, 0xbb000000, v17
	v_fmac_f32_e32 v110, v61, v61
	v_fmac_f32_e32 v34, 0xbb000000, v17
	v_fmac_f32_e32 v110, v34, v34
	v_fmac_f32_e32 v30, 0xbb000000, v17
	v_fmac_f32_e32 v110, v30, v30
	v_fmac_f32_e32 v35, 0xbb000000, v17
	v_fmac_f32_e32 v110, v35, v35
	v_fmac_f32_e32 v31, 0xbb000000, v17
	v_fmac_f32_e32 v110, v31, v31
	v_fmac_f32_e32 v28, 0xbb000000, v17
	v_fmac_f32_e32 v110, v28, v28
	v_fmac_f32_e32 v24, 0xbb000000, v17
	v_fmac_f32_e32 v110, v24, v24
	v_fmac_f32_e32 v29, 0xbb000000, v17
	v_fmac_f32_e32 v110, v29, v29
	v_fmac_f32_e32 v25, 0xbb000000, v17
	v_fmac_f32_e32 v110, v25, v25
	v_fmac_f32_e32 v36, 0xbb000000, v17
	v_fmac_f32_e32 v110, v36, v36
	v_fmac_f32_e32 v38, 0xbb000000, v17
	v_fmac_f32_e32 v110, v38, v38
	v_fmac_f32_e32 v40, 0xbb000000, v17
	v_fmac_f32_e32 v110, v40, v40
	v_fmac_f32_e32 v42, 0xbb000000, v17
	v_fmac_f32_e32 v110, v42, v42
	v_fmac_f32_e32 v160, 0xbb000000, v17
	v_fmac_f32_e32 v110, v160, v160
	v_fmac_f32_e32 v161, 0xbb000000, v17
	v_mul_f32_e32 v16, 0x3b000000, v17
	v_fmac_f32_e32 v110, v161, v161
	v_fmac_f32_e32 v162, 0xbb000000, v17
	v_fmac_f32_e32 v110, v162, v162
	v_fmac_f32_e32 v163, 0xbb000000, v17
	v_pk_add_f32 v[24:25], v[26:27], v[16:17] op_sel_hi:[1,0] neg_lo:[0,1] neg_hi:[0,1]
	v_fmac_f32_e32 v110, v163, v163
	v_pk_mul_f32 v[24:25], v[24:25], v[24:25]
	v_pk_add_f32 v[18:19], v[18:19], v[16:17] op_sel_hi:[1,0] neg_lo:[0,1] neg_hi:[0,1]
	v_add_f32_e32 v25, v25, v110
	v_add_f32_e32 v24, v24, v25
	v_pk_mul_f32 v[18:19], v[18:19], v[18:19]
	v_lshlrev_b32_e32 v35, 2, v45
	v_add_f32_e32 v19, v19, v24
	v_add_f32_e32 v24, v18, v19
	v_pk_add_f32 v[18:19], v[22:23], v[16:17] op_sel_hi:[1,0] neg_lo:[0,1] neg_hi:[0,1]
	s_waitcnt vmcnt(3)
	v_lshlrev_b32_e32 v36, 16, v12
	v_pk_mul_f32 v[18:19], v[18:19], v[18:19]
	v_and_b32_e32 v12, 0xffff0000, v12
	v_add_f32_e32 v19, v19, v24
	v_add_f32_e32 v22, v18, v19
	v_pk_add_f32 v[18:19], v[20:21], v[16:17] op_sel_hi:[1,0] neg_lo:[0,1] neg_hi:[0,1]
	v_fmac_f32_e32 v36, 0xbb000000, v17
	v_pk_mul_f32 v[18:19], v[18:19], v[18:19]
	v_fmac_f32_e32 v12, 0xbb000000, v17
	v_add_f32_e32 v16, v19, v22
	v_add_f32_e32 v16, v18, v16
	ds_bpermute_b32 v18, v164, v16
	v_lshlrev_b32_e32 v34, 1, v44
	v_lshlrev_b32_e32 v37, 16, v13
	v_fmac_f32_e32 v37, 0xbb000000, v17
	v_and_b32_e32 v13, 0xffff0000, v13
	s_waitcnt lgkmcnt(0)
	v_add_f32_e32 v16, v16, v18
	ds_bpermute_b32 v18, v165, v16
	v_fmac_f32_e32 v13, 0xbb000000, v17
	v_lshlrev_b32_e32 v38, 16, v14
	v_fmac_f32_e32 v38, 0xbb000000, v17
	v_and_b32_e32 v14, 0xffff0000, v14
	s_waitcnt lgkmcnt(0)
	v_add_f32_e32 v16, v16, v18
	v_fmamk_f32 v16, v16, 0x3b000000, v220
	v_cmp_gt_f32_e32 vcc, s13, v16
	v_mul_f32_e32 v18, 0x4b800000, v16
	v_fmac_f32_e32 v14, 0xbb000000, v17
	v_cndmask_b32_e32 v16, v16, v18, vcc
	v_rsq_f32_e32 v16, v16
	v_lshlrev_b32_e32 v39, 16, v15
	v_fmac_f32_e32 v39, 0xbb000000, v17
	v_and_b32_e32 v15, 0xffff0000, v15
	v_mul_f32_e32 v18, 0x45800000, v16
	v_cndmask_b32_e32 v16, v16, v18, vcc
	v_mov_b32_e32 v174, v17
	v_mov_b32_e32 v175, v16
.Lsgu_join:
	global_load_dwordx4 v[18:21], v35, s[40:41] offset:16
	global_load_dwordx4 v[22:25], v35, s[40:41]
	global_load_dwordx4 v[26:29], v35, s[46:47] offset:16
	global_load_dwordx4 v[30:33], v35, s[46:47]
	v_mul_f32_e32 v36, v36, v16
	v_mul_f32_e32 v12, v12, v16
	v_fmac_f32_e32 v15, 0xbb000000, v17
	v_or_b32_e32 v131, s36, v132
	v_or_b32_e32 v142, 16, v131
	v_or_b32_e32 v141, 32, v131
	v_or_b32_e32 v140, 48, v131
	v_or_b32_e32 v139, 64, v131
	v_or_b32_e32 v138, 0x50, v131
	v_or_b32_e32 v137, 0x60, v131
	v_or_b32_e32 v133, 0x70, v131
	s_waitcnt vmcnt(0)
	v_fma_f32 v22, v22, v36, v30
	v_mul_u32_u24_e32 v30, 0x110, v45
	v_fma_f32 v12, v23, v12, v31
	v_add3_u32 v30, 0, v34, v30
	v_cvt_pk_bf16_f32 v12, v12, s0
	ds_write_b16 v30, v12 offset:272
	v_mul_f32_e32 v12, v37, v16
	v_fma_f32 v12, v24, v12, v32
	v_cvt_pk_bf16_f32 v12, v12, s0
	ds_write_b16 v30, v12 offset:544
	v_mul_f32_e32 v12, v13, v16
	v_fmac_f32_e32 v33, v25, v12
	v_cvt_pk_bf16_f32 v12, v33, s0
	ds_write_b16 v30, v12 offset:816
	v_mul_f32_e32 v12, v38, v16
	v_fma_f32 v12, v18, v12, v26
	v_cvt_pk_bf16_f32 v12, v12, s0
	ds_write_b16 v30, v12 offset:1088
	v_mul_f32_e32 v12, v14, v16
	v_fma_f32 v12, v19, v12, v27
	v_cvt_pk_bf16_f32 v12, v12, s0
	ds_write_b16 v30, v12 offset:1360
	v_mul_f32_e32 v12, v39, v16
	v_fma_f32 v12, v20, v12, v28
	v_cvt_pk_bf16_f32 v12, v12, s0
	ds_write_b16 v30, v12 offset:1632
	v_mul_f32_e32 v12, v15, v16
	v_fmac_f32_e32 v29, v21, v12
	v_cvt_pk_bf16_f32 v22, v22, s0
	v_cvt_pk_bf16_f32 v12, v29, s0
	ds_write_b16 v30, v22
	ds_write_b16 v30, v12 offset:1904
	global_load_dwordx4 v[12:15], v35, s[40:41] offset:144
	global_load_dwordx4 v[18:21], v35, s[40:41] offset:128
	global_load_dwordx4 v[22:25], v35, s[46:47] offset:144
	global_load_dwordx4 v[26:29], v35, s[46:47] offset:128
	v_lshlrev_b32_e32 v31, 16, v8
	v_and_b32_e32 v8, 0xffff0000, v8
	v_fmac_f32_e32 v8, 0xbb000000, v17
	v_mul_f32_e32 v8, v8, v16
	v_lshlrev_b32_e32 v32, 16, v9
	v_fmac_f32_e32 v32, 0xbb000000, v17
	v_and_b32_e32 v9, 0xffff0000, v9
	v_fmac_f32_e32 v9, 0xbb000000, v17
	v_lshlrev_b32_e32 v33, 16, v10
	v_fmac_f32_e32 v33, 0xbb000000, v17
	v_and_b32_e32 v10, 0xffff0000, v10
	v_fmac_f32_e32 v10, 0xbb000000, v17
	v_lshlrev_b32_e32 v34, 16, v11
	v_fmac_f32_e32 v34, 0xbb000000, v17
	v_and_b32_e32 v11, 0xffff0000, v11
	v_fmac_f32_e32 v31, 0xbb000000, v17
	v_fmac_f32_e32 v11, 0xbb000000, v17
	v_mul_f32_e32 v31, v31, v16
	s_waitcnt vmcnt(0)
	v_fma_f32 v8, v19, v8, v27
	v_cvt_pk_bf16_f32 v8, v8, s0
	ds_write_b16 v30, v8 offset:8976
	v_mul_f32_e32 v8, v32, v16
	v_fma_f32 v8, v20, v8, v28
	v_cvt_pk_bf16_f32 v8, v8, s0
	ds_write_b16 v30, v8 offset:9248
	v_mul_f32_e32 v8, v9, v16
	v_fmac_f32_e32 v29, v21, v8
	v_cvt_pk_bf16_f32 v8, v29, s0
	ds_write_b16 v30, v8 offset:9520
	v_mul_f32_e32 v8, v33, v16
	v_fma_f32 v8, v12, v8, v22
	v_cvt_pk_bf16_f32 v8, v8, s0
	ds_write_b16 v30, v8 offset:9792
	v_mul_f32_e32 v8, v10, v16
	v_fma_f32 v8, v13, v8, v23
	v_cvt_pk_bf16_f32 v8, v8, s0
	ds_write_b16 v30, v8 offset:10064
	v_mul_f32_e32 v8, v34, v16
	v_fma_f32 v8, v14, v8, v24
	v_cvt_pk_bf16_f32 v8, v8, s0
	ds_write_b16 v30, v8 offset:10336
	v_mul_f32_e32 v8, v11, v16
	v_fma_f32 v18, v18, v31, v26
	v_fmac_f32_e32 v25, v15, v8
	v_cvt_pk_bf16_f32 v18, v18, s0
	v_cvt_pk_bf16_f32 v8, v25, s0
	ds_write_b16 v30, v18 offset:8704
	ds_write_b16 v30, v8 offset:10608
	global_load_dwordx4 v[8:11], v35, s[40:41] offset:272
	global_load_dwordx4 v[12:15], v35, s[40:41] offset:256
	global_load_dwordx4 v[18:21], v35, s[46:47] offset:272
	global_load_dwordx4 v[22:25], v35, s[46:47] offset:256
	v_lshlrev_b32_e32 v26, 16, v4
	v_and_b32_e32 v4, 0xffff0000, v4
	v_fmac_f32_e32 v4, 0xbb000000, v17
	v_mul_f32_e32 v4, v4, v16
	v_lshlrev_b32_e32 v27, 16, v5
	v_fmac_f32_e32 v27, 0xbb000000, v17
	v_and_b32_e32 v5, 0xffff0000, v5
	v_fmac_f32_e32 v5, 0xbb000000, v17
	v_lshlrev_b32_e32 v28, 16, v6
	v_fmac_f32_e32 v28, 0xbb000000, v17
	v_and_b32_e32 v6, 0xffff0000, v6
	v_fmac_f32_e32 v6, 0xbb000000, v17
	v_lshlrev_b32_e32 v29, 16, v7
	v_fmac_f32_e32 v29, 0xbb000000, v17
	v_and_b32_e32 v7, 0xffff0000, v7
	v_fmac_f32_e32 v26, 0xbb000000, v17
	v_fmac_f32_e32 v7, 0xbb000000, v17
	v_mul_f32_e32 v26, v26, v16
	s_waitcnt vmcnt(0)
	v_fma_f32 v4, v13, v4, v23
	v_cvt_pk_bf16_f32 v4, v4, s0
	ds_write_b16 v30, v4 offset:17680
	v_mul_f32_e32 v4, v27, v16
	v_fma_f32 v4, v14, v4, v24
	v_cvt_pk_bf16_f32 v4, v4, s0
	ds_write_b16 v30, v4 offset:17952
	v_mul_f32_e32 v4, v5, v16
	v_fmac_f32_e32 v25, v15, v4
	v_cvt_pk_bf16_f32 v4, v25, s0
	ds_write_b16 v30, v4 offset:18224
	v_mul_f32_e32 v4, v28, v16
	v_fma_f32 v4, v8, v4, v18
	v_cvt_pk_bf16_f32 v4, v4, s0
	ds_write_b16 v30, v4 offset:18496
	v_mul_f32_e32 v4, v6, v16
	v_fma_f32 v4, v9, v4, v19
	v_cvt_pk_bf16_f32 v4, v4, s0
	ds_write_b16 v30, v4 offset:18768
	v_mul_f32_e32 v4, v29, v16
	v_fma_f32 v4, v10, v4, v20
	v_cvt_pk_bf16_f32 v4, v4, s0
	ds_write_b16 v30, v4 offset:19040
	v_mul_f32_e32 v4, v7, v16
	v_fma_f32 v12, v12, v26, v22
	v_fmac_f32_e32 v21, v11, v4
	v_cvt_pk_bf16_f32 v12, v12, s0
	v_cvt_pk_bf16_f32 v4, v21, s0
	ds_write_b16 v30, v12 offset:17408
	ds_write_b16 v30, v4 offset:19312
	global_load_dwordx4 v[4:7], v35, s[40:41] offset:400
	global_load_dwordx4 v[8:11], v35, s[40:41] offset:384
	global_load_dwordx4 v[12:15], v35, s[46:47] offset:400
	global_load_dwordx4 v[18:21], v35, s[46:47] offset:384
	v_lshlrev_b32_e32 v22, 16, v0
	v_and_b32_e32 v0, 0xffff0000, v0
	v_fmac_f32_e32 v0, 0xbb000000, v17
	v_mul_f32_e32 v0, v0, v16
	v_lshlrev_b32_e32 v23, 16, v1
	v_fmac_f32_e32 v23, 0xbb000000, v17
	v_and_b32_e32 v1, 0xffff0000, v1
	v_fmac_f32_e32 v1, 0xbb000000, v17
	v_lshlrev_b32_e32 v24, 16, v2
	v_fmac_f32_e32 v24, 0xbb000000, v17
	v_and_b32_e32 v2, 0xffff0000, v2
	v_fmac_f32_e32 v2, 0xbb000000, v17
	v_lshlrev_b32_e32 v25, 16, v3
	v_fmac_f32_e32 v25, 0xbb000000, v17
	v_and_b32_e32 v3, 0xffff0000, v3
	v_fmac_f32_e32 v3, 0xbb000000, v17
	v_fmac_f32_e32 v22, 0xbb000000, v17
	v_mul_f32_e32 v22, v22, v16
	v_and_b32_e32 v17, -16, v130
	s_waitcnt vmcnt(0)
	v_fma_f32 v0, v9, v0, v19
	v_cvt_pk_bf16_f32 v0, v0, s0
	ds_write_b16 v30, v0 offset:26384
	v_mul_f32_e32 v0, v23, v16
	v_fma_f32 v0, v10, v0, v20
	v_cvt_pk_bf16_f32 v0, v0, s0
	ds_write_b16 v30, v0 offset:26656
	v_mul_f32_e32 v0, v1, v16
	v_fmac_f32_e32 v21, v11, v0
	v_cvt_pk_bf16_f32 v0, v21, s0
	ds_write_b16 v30, v0 offset:26928
	v_mul_f32_e32 v0, v24, v16
	v_fma_f32 v0, v4, v0, v12
	v_cvt_pk_bf16_f32 v0, v0, s0
	ds_write_b16 v30, v0 offset:27200
	v_mul_f32_e32 v0, v2, v16
	v_fma_f32 v0, v5, v0, v13
	v_cvt_pk_bf16_f32 v0, v0, s0
	ds_write_b16 v30, v0 offset:27472
	v_mul_f32_e32 v0, v25, v16
	v_fma_f32 v0, v6, v0, v14
	v_cvt_pk_bf16_f32 v0, v0, s0
	ds_write_b16 v30, v0 offset:27744
	v_mul_f32_e32 v0, v3, v16
	v_ashrrev_i32_e32 v4, 4, v130
	v_fmac_f32_e32 v15, v7, v0
	v_lshlrev_b32_e32 v92, 2, v4
	v_cvt_pk_bf16_f32 v0, v15, s0
	v_ashrrev_i32_e32 v93, 31, v92
	ds_write_b16 v30, v0 offset:28016
	v_lshl_add_u64 v[0:1], v[92:93], 1, s[8:9]
	v_mad_u64_u32 v[2:3], s[8:9], v131, s14, v[0:1]
	v_mad_i32_i24 v3, s37, v225, v3
	global_load_dwordx2 v[126:127], v[2:3], off offset:1024
	v_add_co_u32_e32 v2, vcc, s15, v2
	v_fma_f32 v8, v8, v22, v18
	s_nop 0
	v_addc_co_u32_e32 v3, vcc, 0, v3, vcc
	global_load_dwordx2 v[128:129], v[2:3], off offset:2048
	v_mad_u64_u32 v[2:3], s[8:9], v142, s14, v[0:1]
	v_mad_i32_i24 v3, s37, v225, v3
	global_load_dwordx2 v[122:123], v[2:3], off offset:1024
	v_add_co_u32_e32 v2, vcc, s15, v2
	v_cvt_pk_bf16_f32 v8, v8, s0
	s_nop 0
	v_addc_co_u32_e32 v3, vcc, 0, v3, vcc
	global_load_dwordx2 v[124:125], v[2:3], off offset:2048
	v_mad_u64_u32 v[2:3], s[8:9], v141, s14, v[0:1]
	v_mad_i32_i24 v3, s37, v225, v3
	global_load_dwordx2 v[118:119], v[2:3], off offset:1024
	v_add_co_u32_e32 v2, vcc, s15, v2
	ds_write_b16 v30, v8 offset:26112
	s_nop 0
	v_addc_co_u32_e32 v3, vcc, 0, v3, vcc
	global_load_dwordx2 v[120:121], v[2:3], off offset:2048
	v_mad_u64_u32 v[2:3], s[8:9], v140, s14, v[0:1]
	v_mad_i32_i24 v3, s37, v225, v3
	global_load_dwordx2 v[114:115], v[2:3], off offset:1024
	v_add_co_u32_e32 v2, vcc, s15, v2
	v_or_b32_e32 v16, s10, v132
	s_nop 0
	v_addc_co_u32_e32 v3, vcc, 0, v3, vcc
	global_load_dwordx2 v[116:117], v[2:3], off offset:2048
	v_mad_u64_u32 v[2:3], s[8:9], v139, s14, v[0:1]
	v_mad_i32_i24 v3, s37, v225, v3
	global_load_dwordx2 v[110:111], v[2:3], off offset:1024
	v_add_co_u32_e32 v2, vcc, s15, v2
	v_or_b32_e32 v132, s60, v132
	s_nop 0
	v_addc_co_u32_e32 v3, vcc, 0, v3, vcc
	global_load_dwordx2 v[112:113], v[2:3], off offset:2048
	v_mad_u64_u32 v[2:3], s[8:9], v138, s14, v[0:1]
	v_mad_i32_i24 v3, s37, v225, v3
	global_load_dwordx2 v[106:107], v[2:3], off offset:1024
	v_add_co_u32_e32 v2, vcc, s15, v2
	v_lshlrev_b32_e32 v136, 2, v132
	s_nop 0
	v_addc_co_u32_e32 v3, vcc, 0, v3, vcc
	global_load_dwordx2 v[108:109], v[2:3], off offset:2048
	v_mad_u64_u32 v[2:3], s[8:9], v137, s14, v[0:1]
	v_mad_u64_u32 v[0:1], s[8:9], v133, s14, v[0:1]
	v_mad_i32_i24 v3, s37, v225, v3
	v_mad_i32_i24 v1, s37, v225, v1
	global_load_dwordx2 v[100:101], v[2:3], off offset:1024
	global_load_dwordx2 v[96:97], v[0:1], off offset:1024
	v_add_co_u32_e32 v2, vcc, s15, v2
	s_add_u32 s8, s3, s7
	s_nop 0
	v_addc_co_u32_e32 v3, vcc, 0, v3, vcc
	v_add_co_u32_e32 v0, vcc, s15, v0
	s_addc_u32 s9, s11, 0
	s_nop 0
	v_addc_co_u32_e32 v1, vcc, 0, v1, vcc
	global_load_dwordx2 v[98:99], v[0:1], off offset:2048
	v_lshlrev_b32_e32 v0, 3, v4
	v_ashrrev_i32_e32 v1, 31, v0
	v_lshl_add_u64 v[0:1], v[0:1], 1, s[8:9]
	v_lshl_add_u64 v[0:1], v[0:1], 0, v[194:195]
	global_load_dwordx2 v[104:105], v[2:3], off offset:2048
	global_load_dwordx4 v[144:147], v[0:1], off
	v_add_co_u32_e32 v2, vcc, s4, v0
	s_movk_i32 s7, 0x4000
	s_nop 0
	v_addc_co_u32_e32 v3, vcc, 0, v1, vcc
	global_load_dwordx4 v[88:91], v[2:3], off offset:-4096
	global_load_dwordx4 v[80:83], v[2:3], off
	global_load_dwordx4 v[84:87], v[2:3], off offset:64
	v_add_co_u32_e32 v2, vcc, s35, v0
	s_waitcnt vmcnt(18)
	v_lshlrev_b32_e32 v143, 16, v128
	v_addc_co_u32_e32 v3, vcc, 0, v1, vcc
	v_add_co_u32_e32 v4, vcc, s7, v0
	s_movk_i32 s7, 0x5000
	s_nop 0
	v_addc_co_u32_e32 v5, vcc, 0, v1, vcc
	global_load_dwordx4 v[72:75], v[4:5], off offset:-4096
	global_load_dwordx4 v[76:79], v[2:3], off offset:64
	global_load_dwordx4 v[60:63], v[4:5], off
	global_load_dwordx4 v[64:67], v[4:5], off offset:64
	global_load_dwordx4 v[68:71], v[4:5], off offset:128
	v_add_co_u32_e32 v2, vcc, s7, v0
	s_movk_i32 s7, 0x7000
	s_nop 0
	v_addc_co_u32_e32 v3, vcc, 0, v1, vcc
	v_add_co_u32_e32 v4, vcc, s95, v0
	v_and_b32_e32 v128, 0xffff0000, v128
	s_nop 0
	v_addc_co_u32_e32 v5, vcc, 0, v1, vcc
	v_add_co_u32_e32 v12, vcc, s7, v0
	s_movk_i32 s7, 0x110
	v_mul_lo_u32 v16, v16, s7
	v_addc_co_u32_e32 v13, vcc, 0, v1, vcc
	v_add3_u32 v28, 0, v16, v17
	global_load_dwordx4 v[48:51], v[4:5], off offset:-4096
	global_load_dwordx4 v[52:55], v[2:3], off offset:64
	global_load_dwordx4 v[56:59], v[2:3], off offset:128
	global_load_dwordx4 v[32:35], v[4:5], off
	global_load_dwordx4 v[36:39], v[4:5], off offset:64
	global_load_dwordx4 v[40:43], v[4:5], off offset:128
	global_load_dwordx4 v[44:47], v[4:5], off offset:192
	s_nop 0
	global_load_dwordx4 v[0:3], v[12:13], off
	global_load_dwordx4 v[4:7], v[12:13], off offset:64
	global_load_dwordx4 v[8:11], v[12:13], off offset:128
	s_nop 0
	global_load_dwordx4 v[12:15], v[12:13], off offset:192
	s_waitcnt lgkmcnt(0)
	s_barrier
	ds_read_b128 v[16:19], v28
	ds_read_b128 v[20:23], v28 offset:64
	ds_read_b128 v[24:27], v28 offset:128
	ds_read_b128 v[28:31], v28 offset:192
	global_load_dword v132, v136, s[0:1]
	global_load_dword v160, v136, s[0:1] offset:64
	global_load_dword v162, v136, s[0:1] offset:128
	global_load_dword v164, v136, s[0:1] offset:192
	global_load_dword v166, v136, s[0:1] offset:256
	global_load_dword v168, v136, s[0:1] offset:320
	global_load_dword v170, v136, s[0:1] offset:384
	global_load_dword v172, v136, s[0:1] offset:448
	s_add_i32 s7, s60, s10
	v_add_u32_e32 v92, s7, v92
	v_ashrrev_i32_e32 v93, 31, v92
	v_lshl_add_u64 v[102:103], v[92:93], 1, s[82:83]
	s_waitcnt vmcnt(27) lgkmcnt(3)
	v_mfma_f32_16x16x32_bf16 v[92:95], v[16:19], v[144:147], 0
	v_mul_f32_e32 v134, 0xbfb8aa3b, v143
	v_lshlrev_b32_e32 v144, 16, v126
	v_and_b32_e32 v145, 0xffff0000, v126
	v_mul_f32_e32 v126, 0xbfb8aa3b, v128
	v_exp_f32_e32 v134, v134
	v_exp_f32_e32 v135, v126
	v_mad_u64_u32 v[130:131], s[8:9], v131, s14, v[102:103]
	v_mad_i32_i24 v131, s37, v225, v131
	v_pk_add_f32 v[134:135], v[134:135], 1.0 op_sel_hi:[1,0]
	s_waitcnt vmcnt(26)
	v_mfma_f32_16x16x32_bf16 v[88:91], v[16:19], v[88:91], 0
	s_add_i32 s65, s65, s98
	s_waitcnt vmcnt(25)
	v_mfma_f32_16x16x32_bf16 v[80:83], v[16:19], v[80:83], 0
	s_add_i32 s64, s64, s99
	s_cmp_gt_i32 s65, s88
	s_waitcnt vmcnt(0)
	v_pk_add_f32 v[92:93], v[92:93], v[132:133] op_sel_hi:[1,0]
	s_nop 0
	v_pk_mul_f32 v[92:93], v[92:93], v[144:145]
	v_rcp_f32_e32 v144, v135
	v_pk_add_f32 v[94:95], v[94:95], v[132:133] op_sel_hi:[1,0]
	s_waitcnt lgkmcnt(2)
	v_mfma_f32_16x16x32_bf16 v[80:83], v[20:23], v[84:87], v[80:83]
	v_lshlrev_b32_e32 v87, 16, v120
	v_mul_f32_e32 v126, v128, v144
	v_mov_b32_e32 v135, v126
	v_rcp_f32_e32 v128, v134
	v_mfma_f32_16x16x32_bf16 v[72:75], v[16:19], v[72:75], 0
	v_mad_u64_u32 v[84:85], s[8:9], v141, s14, v[102:103]
	v_mul_f32_e32 v126, v143, v128
	v_mov_b32_e32 v134, v126
	v_pk_mul_f32 v[92:93], v[134:135], v[92:93]
	v_lshlrev_b32_e32 v134, 16, v129
	v_and_b32_e32 v135, 0xffff0000, v129
	v_mul_f32_e32 v126, 0xbfb8aa3b, v134
	v_lshlrev_b32_e32 v128, 16, v127
	v_and_b32_e32 v129, 0xffff0000, v127
	v_mul_f32_e32 v127, 0xbfb8aa3b, v135
	v_exp_f32_e32 v126, v126
	v_exp_f32_e32 v127, v127
	v_pk_mul_f32 v[94:95], v[94:95], v[128:129]
	v_cvt_pk_bf16_f32 v92, v92, v93
	v_mad_i32_i24 v85, s37, v225, v85
	v_pk_add_f32 v[126:127], v[126:127], 1.0 op_sel_hi:[1,0]
	v_mfma_f32_16x16x32_bf16 v[72:75], v[20:23], v[76:79], v[72:75]
	v_rcp_f32_e32 v129, v127
	v_lshlrev_b32_e32 v79, 16, v116
	v_mfma_f32_16x16x32_bf16 v[60:63], v[16:19], v[60:63], 0
	v_mad_u64_u32 v[76:77], s[8:9], v140, s14, v[102:103]
	v_mul_f32_e32 v128, v135, v129
	v_mov_b32_e32 v127, v128
	v_rcp_f32_e32 v129, v126
	v_mad_i32_i24 v77, s37, v225, v77
	v_mfma_f32_16x16x32_bf16 v[60:63], v[20:23], v[64:67], v[60:63]
	v_lshlrev_b32_e32 v67, 16, v112
	v_mul_f32_e32 v128, v134, v129
	v_mov_b32_e32 v126, v128
	v_pk_mul_f32 v[94:95], v[126:127], v[94:95]
	v_lshlrev_b32_e32 v128, 16, v122
	v_cvt_pk_bf16_f32 v93, v94, v95
	global_store_dwordx2 v[130:131], v[92:93], off offset:1024
	v_lshlrev_b32_e32 v95, 16, v124
	v_and_b32_e32 v124, 0xffff0000, v124
	v_mul_f32_e32 v126, 0xbfb8aa3b, v95
	v_and_b32_e32 v129, 0xffff0000, v122
	v_mul_f32_e32 v122, 0xbfb8aa3b, v124
	v_exp_f32_e32 v126, v126
	v_exp_f32_e32 v127, v122
	v_mad_u64_u32 v[92:93], s[8:9], v142, s14, v[102:103]
	v_mad_i32_i24 v93, s37, v225, v93
	v_pk_add_f32 v[126:127], v[126:127], 1.0 op_sel_hi:[1,0]
	s_waitcnt lgkmcnt(1)
	v_mfma_f32_16x16x32_bf16 v[60:63], v[24:27], v[68:71], v[60:63]
	v_mul_f32_e32 v68, 0xbfb8aa3b, v67
	v_exp_f32_e32 v68, v68
	v_lshlrev_b32_e32 v70, 16, v110
	v_and_b32_e32 v71, 0xffff0000, v110
	v_mfma_f32_16x16x32_bf16 v[48:51], v[16:19], v[48:51], 0
	v_mad_u64_u32 v[64:65], s[8:9], v139, s14, v[102:103]
	v_mad_i32_i24 v65, s37, v225, v65
	v_mfma_f32_16x16x32_bf16 v[48:51], v[20:23], v[52:55], v[48:51]
	v_lshlrev_b32_e32 v55, 16, v108
	v_mad_u64_u32 v[52:53], s[8:9], v138, s14, v[102:103]
	v_mfma_f32_16x16x32_bf16 v[48:51], v[24:27], v[56:59], v[48:51]
	v_mul_f32_e32 v56, 0xbfb8aa3b, v55
	v_exp_f32_e32 v56, v56
	v_lshlrev_b32_e32 v58, 16, v106
	v_and_b32_e32 v59, 0xffff0000, v106
	v_mfma_f32_16x16x32_bf16 v[32:35], v[16:19], v[32:35], 0
	v_mad_i32_i24 v53, s37, v225, v53
	v_pk_add_f32 v[88:89], v[88:89], v[160:161] op_sel_hi:[1,0]
	s_nop 0
	v_pk_mul_f32 v[88:89], v[88:89], v[128:129]
	v_rcp_f32_e32 v128, v127
	v_mfma_f32_16x16x32_bf16 v[32:35], v[20:23], v[36:39], v[32:35]
	v_lshlrev_b32_e32 v39, 16, v104
	v_mad_u64_u32 v[36:37], s[8:9], v137, s14, v[102:103]
	v_mul_f32_e32 v122, v124, v128
	v_mov_b32_e32 v127, v122
	v_rcp_f32_e32 v124, v126
	v_mfma_f32_16x16x32_bf16 v[32:35], v[24:27], v[40:43], v[32:35]
	v_mul_f32_e32 v40, 0xbfb8aa3b, v39
	v_exp_f32_e32 v40, v40
	v_mul_f32_e32 v122, v95, v124
	v_mov_b32_e32 v126, v122
	v_pk_mul_f32 v[88:89], v[126:127], v[88:89]
	v_lshlrev_b32_e32 v126, 16, v125
	v_and_b32_e32 v127, 0xffff0000, v125
	v_mul_f32_e32 v95, 0xbfb8aa3b, v126
	v_pk_add_f32 v[90:91], v[90:91], v[160:161] op_sel_hi:[1,0]
	v_mul_f32_e32 v94, 0xbfb8aa3b, v127
	v_exp_f32_e32 v122, v95
	v_lshlrev_b32_e32 v124, 16, v123
	v_and_b32_e32 v125, 0xffff0000, v123
	v_exp_f32_e32 v123, v94
	v_pk_mul_f32 v[90:91], v[90:91], v[124:125]
	v_cvt_pk_bf16_f32 v88, v88, v89
	s_waitcnt lgkmcnt(0)
	v_mfma_f32_16x16x32_bf16 v[32:35], v[28:31], v[44:47], v[32:35]
	v_add_f32_e64 v94, v122, 1.0
	v_add_f32_e64 v95, v123, 1.0
	v_and_b32_e32 v44, 0xffff0000, v104
	v_rcp_f32_e32 v123, v95
	v_mul_f32_e32 v41, 0xbfb8aa3b, v44
	v_exp_f32_e32 v41, v41
	v_lshlrev_b32_e32 v42, 16, v100
	v_mul_f32_e32 v122, v127, v123
	v_mov_b32_e32 v95, v122
	v_rcp_f32_e32 v123, v94
	v_and_b32_e32 v43, 0xffff0000, v100
	v_pk_add_f32 v[40:41], v[40:41], 1.0 op_sel_hi:[1,0]
	v_mfma_f32_16x16x32_bf16 v[0:3], v[16:19], v[0:3], 0
	v_mul_f32_e32 v122, v126, v123
	v_mov_b32_e32 v94, v122
	v_pk_mul_f32 v[90:91], v[94:95], v[90:91]
	v_mad_i32_i24 v37, s37, v225, v37
	v_cvt_pk_bf16_f32 v89, v90, v91
	global_store_dwordx2 v[92:93], v[88:89], off offset:1024
	v_and_b32_e32 v92, 0xffff0000, v120
	v_mul_f32_e32 v88, 0xbfb8aa3b, v87
	v_mul_f32_e32 v89, 0xbfb8aa3b, v92
	v_exp_f32_e32 v88, v88
	v_exp_f32_e32 v89, v89
	v_lshlrev_b32_e32 v90, 16, v118
	v_and_b32_e32 v91, 0xffff0000, v118
	v_mfma_f32_16x16x32_bf16 v[0:3], v[20:23], v[4:7], v[0:3]
	v_add_f32_e64 v88, v88, 1.0
	v_add_f32_e64 v89, v89, 1.0
	v_lshlrev_b32_e32 v7, 16, v98
	v_mad_u64_u32 v[4:5], s[8:9], v133, s14, v[102:103]
	v_mfma_f32_16x16x32_bf16 v[0:3], v[24:27], v[8:11], v[0:3]
	v_mul_f32_e32 v8, 0xbfb8aa3b, v7
	v_exp_f32_e32 v8, v8
	v_lshlrev_b32_e32 v10, 16, v96
	v_mfma_f32_16x16x32_bf16 v[0:3], v[28:31], v[12:15], v[0:3]
	v_and_b32_e32 v12, 0xffff0000, v98
	v_mul_f32_e32 v9, 0xbfb8aa3b, v12
	v_exp_f32_e32 v9, v9
	v_and_b32_e32 v11, 0xffff0000, v96
	v_mad_i32_i24 v5, s37, v225, v5
	v_pk_add_f32 v[8:9], v[8:9], 1.0 op_sel_hi:[1,0]
	v_pk_add_f32 v[80:81], v[80:81], v[162:163] op_sel_hi:[1,0]
	s_nop 0
	v_pk_mul_f32 v[80:81], v[80:81], v[90:91]
	v_rcp_f32_e32 v91, v89
	s_nop 0
	v_mul_f32_e32 v90, v92, v91
	v_mov_b32_e32 v89, v90
	v_rcp_f32_e32 v91, v88
	s_nop 0
	v_mul_f32_e32 v90, v87, v91
	v_lshlrev_b32_e32 v92, 16, v121
	v_mov_b32_e32 v88, v90
	v_and_b32_e32 v93, 0xffff0000, v121
	v_mul_f32_e32 v87, 0xbfb8aa3b, v92
	v_pk_add_f32 v[82:83], v[82:83], v[162:163] op_sel_hi:[1,0]
	v_mul_f32_e32 v86, 0xbfb8aa3b, v93
	v_pk_mul_f32 v[80:81], v[88:89], v[80:81]
	v_exp_f32_e32 v88, v87
	v_exp_f32_e32 v89, v86
	v_lshlrev_b32_e32 v90, 16, v119
	v_and_b32_e32 v91, 0xffff0000, v119
	v_pk_mul_f32 v[82:83], v[82:83], v[90:91]
	v_pk_add_f32 v[86:87], v[88:89], 1.0 op_sel_hi:[1,0]
	v_cvt_pk_bf16_f32 v80, v80, v81
	v_rcp_f32_e32 v89, v87
	s_nop 0
	v_mul_f32_e32 v88, v93, v89
	v_mov_b32_e32 v87, v88
	v_rcp_f32_e32 v89, v86
	s_nop 0
	v_mul_f32_e32 v88, v92, v89
	v_mov_b32_e32 v86, v88
	v_pk_mul_f32 v[82:83], v[86:87], v[82:83]
	s_nop 0
	v_cvt_pk_bf16_f32 v81, v82, v83
	global_store_dwordx2 v[84:85], v[80:81], off offset:1024
	v_and_b32_e32 v84, 0xffff0000, v116
	v_mul_f32_e32 v80, 0xbfb8aa3b, v79
	v_mul_f32_e32 v81, 0xbfb8aa3b, v84
	v_exp_f32_e32 v80, v80
	v_exp_f32_e32 v81, v81
	v_lshlrev_b32_e32 v82, 16, v114
	v_and_b32_e32 v83, 0xffff0000, v114
	v_pk_add_f32 v[80:81], v[80:81], 1.0 op_sel_hi:[1,0]
	v_pk_add_f32 v[72:73], v[72:73], v[164:165] op_sel_hi:[1,0]
	s_nop 0
	v_pk_mul_f32 v[72:73], v[72:73], v[82:83]
	v_rcp_f32_e32 v83, v81
	s_nop 0
	v_mul_f32_e32 v82, v84, v83
	v_mov_b32_e32 v81, v82
	v_rcp_f32_e32 v83, v80
	s_nop 0
	v_mul_f32_e32 v82, v79, v83
	v_lshlrev_b32_e32 v84, 16, v117
	v_mov_b32_e32 v80, v82
	v_and_b32_e32 v85, 0xffff0000, v117
	v_mul_f32_e32 v79, 0xbfb8aa3b, v84
	v_pk_add_f32 v[74:75], v[74:75], v[164:165] op_sel_hi:[1,0]
	v_mul_f32_e32 v78, 0xbfb8aa3b, v85
	v_pk_mul_f32 v[72:73], v[80:81], v[72:73]
	v_exp_f32_e32 v80, v79
	v_exp_f32_e32 v81, v78
	v_lshlrev_b32_e32 v82, 16, v115
	v_and_b32_e32 v83, 0xffff0000, v115
	v_pk_mul_f32 v[74:75], v[74:75], v[82:83]
	v_pk_add_f32 v[78:79], v[80:81], 1.0 op_sel_hi:[1,0]
	v_cvt_pk_bf16_f32 v72, v72, v73
	v_rcp_f32_e32 v81, v79
	s_nop 0
	v_mul_f32_e32 v80, v85, v81
	v_mov_b32_e32 v79, v80
	v_rcp_f32_e32 v81, v78
	s_nop 0
	v_mul_f32_e32 v80, v84, v81
	v_mov_b32_e32 v78, v80
	v_pk_mul_f32 v[74:75], v[78:79], v[74:75]
	s_nop 0
	v_cvt_pk_bf16_f32 v73, v74, v75
	global_store_dwordx2 v[76:77], v[72:73], off offset:1024
	v_and_b32_e32 v72, 0xffff0000, v112
	v_mul_f32_e32 v69, 0xbfb8aa3b, v72
	v_exp_f32_e32 v69, v69
	v_pk_add_f32 v[60:61], v[60:61], v[166:167] op_sel_hi:[1,0]
	v_pk_add_f32 v[68:69], v[68:69], 1.0 op_sel_hi:[1,0]
	v_pk_mul_f32 v[60:61], v[60:61], v[70:71]
	v_rcp_f32_e32 v71, v69
	s_nop 0
	v_mul_f32_e32 v70, v72, v71
	v_mov_b32_e32 v69, v70
	v_rcp_f32_e32 v71, v68
	s_nop 0
	v_mul_f32_e32 v70, v67, v71
	v_lshlrev_b32_e32 v72, 16, v113
	v_mov_b32_e32 v68, v70
	v_and_b32_e32 v73, 0xffff0000, v113
	v_mul_f32_e32 v67, 0xbfb8aa3b, v72
	v_pk_add_f32 v[62:63], v[62:63], v[166:167] op_sel_hi:[1,0]
	v_mul_f32_e32 v66, 0xbfb8aa3b, v73
	v_pk_mul_f32 v[60:61], v[68:69], v[60:61]
	v_exp_f32_e32 v68, v67
	v_exp_f32_e32 v69, v66
	v_lshlrev_b32_e32 v70, 16, v111
	v_and_b32_e32 v71, 0xffff0000, v111
	v_pk_mul_f32 v[62:63], v[62:63], v[70:71]
	v_pk_add_f32 v[66:67], v[68:69], 1.0 op_sel_hi:[1,0]
	v_cvt_pk_bf16_f32 v60, v60, v61
	v_rcp_f32_e32 v69, v67
	s_nop 0
	v_mul_f32_e32 v68, v73, v69
	v_mov_b32_e32 v67, v68
	v_rcp_f32_e32 v69, v66
	s_nop 0
	v_mul_f32_e32 v68, v72, v69
	v_mov_b32_e32 v66, v68
	v_pk_mul_f32 v[62:63], v[66:67], v[62:63]
	s_nop 0
	v_cvt_pk_bf16_f32 v61, v62, v63
	global_store_dwordx2 v[64:65], v[60:61], off offset:1024
	v_and_b32_e32 v60, 0xffff0000, v108
	v_mul_f32_e32 v57, 0xbfb8aa3b, v60
	v_exp_f32_e32 v57, v57
	v_pk_add_f32 v[48:49], v[48:49], v[168:169] op_sel_hi:[1,0]
	v_pk_add_f32 v[56:57], v[56:57], 1.0 op_sel_hi:[1,0]
	v_pk_mul_f32 v[48:49], v[48:49], v[58:59]
	v_rcp_f32_e32 v59, v57
	s_nop 0
	v_mul_f32_e32 v58, v60, v59
	v_mov_b32_e32 v57, v58
	v_rcp_f32_e32 v59, v56
	s_nop 0
	v_mul_f32_e32 v58, v55, v59
	v_lshlrev_b32_e32 v60, 16, v109
	v_mov_b32_e32 v56, v58
	v_and_b32_e32 v61, 0xffff0000, v109
	v_mul_f32_e32 v55, 0xbfb8aa3b, v60
	v_pk_add_f32 v[50:51], v[50:51], v[168:169] op_sel_hi:[1,0]
	v_mul_f32_e32 v54, 0xbfb8aa3b, v61
	v_pk_mul_f32 v[48:49], v[56:57], v[48:49]
	v_exp_f32_e32 v56, v55
	v_exp_f32_e32 v57, v54
	v_lshlrev_b32_e32 v58, 16, v107
	v_and_b32_e32 v59, 0xffff0000, v107
	v_pk_mul_f32 v[50:51], v[50:51], v[58:59]
	v_pk_add_f32 v[54:55], v[56:57], 1.0 op_sel_hi:[1,0]
	v_cvt_pk_bf16_f32 v48, v48, v49
	v_rcp_f32_e32 v57, v55
	s_nop 0
	v_mul_f32_e32 v56, v61, v57
	v_mov_b32_e32 v55, v56
	v_rcp_f32_e32 v57, v54
	s_nop 0
	v_mul_f32_e32 v56, v60, v57
	v_mov_b32_e32 v54, v56
	v_pk_mul_f32 v[50:51], v[54:55], v[50:51]
	s_nop 0
	v_cvt_pk_bf16_f32 v49, v50, v51
	global_store_dwordx2 v[52:53], v[48:49], off offset:1024
	v_pk_add_f32 v[32:33], v[32:33], v[170:171] op_sel_hi:[1,0]
	s_nop 0
	v_pk_mul_f32 v[32:33], v[32:33], v[42:43]
	v_rcp_f32_e32 v43, v41
	s_nop 0
	v_mul_f32_e32 v42, v44, v43
	v_mov_b32_e32 v41, v42
	v_rcp_f32_e32 v43, v40
	s_nop 0
	v_mul_f32_e32 v42, v39, v43
	v_lshlrev_b32_e32 v44, 16, v105
	v_mov_b32_e32 v40, v42
	v_and_b32_e32 v45, 0xffff0000, v105
	v_mul_f32_e32 v39, 0xbfb8aa3b, v44
	v_pk_add_f32 v[34:35], v[34:35], v[170:171] op_sel_hi:[1,0]
	v_mul_f32_e32 v38, 0xbfb8aa3b, v45
	v_pk_mul_f32 v[32:33], v[40:41], v[32:33]
	v_exp_f32_e32 v40, v39
	v_exp_f32_e32 v41, v38
	v_lshlrev_b32_e32 v42, 16, v101
	v_and_b32_e32 v43, 0xffff0000, v101
	v_pk_mul_f32 v[34:35], v[34:35], v[42:43]
	v_pk_add_f32 v[38:39], v[40:41], 1.0 op_sel_hi:[1,0]
	v_cvt_pk_bf16_f32 v32, v32, v33
	v_rcp_f32_e32 v41, v39
	s_nop 0
	v_mul_f32_e32 v40, v45, v41
	v_mov_b32_e32 v39, v40
	v_rcp_f32_e32 v41, v38
	s_nop 0
	v_mul_f32_e32 v40, v44, v41
	v_mov_b32_e32 v38, v40
	v_pk_mul_f32 v[34:35], v[38:39], v[34:35]
	s_nop 0
	v_cvt_pk_bf16_f32 v33, v34, v35
	global_store_dwordx2 v[36:37], v[32:33], off offset:1024
	v_pk_add_f32 v[0:1], v[0:1], v[172:173] op_sel_hi:[1,0]
	s_nop 0
	v_pk_mul_f32 v[0:1], v[0:1], v[10:11]
	v_rcp_f32_e32 v11, v9
	s_nop 0
	v_mul_f32_e32 v10, v12, v11
	v_mov_b32_e32 v9, v10
	v_rcp_f32_e32 v11, v8
	s_nop 0
	v_mul_f32_e32 v10, v7, v11
	v_lshlrev_b32_e32 v12, 16, v99
	v_mov_b32_e32 v8, v10
	v_and_b32_e32 v13, 0xffff0000, v99
	v_mul_f32_e32 v7, 0xbfb8aa3b, v12
	v_pk_add_f32 v[2:3], v[2:3], v[172:173] op_sel_hi:[1,0]
	v_mul_f32_e32 v6, 0xbfb8aa3b, v13
	v_pk_mul_f32 v[0:1], v[8:9], v[0:1]
	v_exp_f32_e32 v8, v7
	v_exp_f32_e32 v9, v6
	v_lshlrev_b32_e32 v10, 16, v97
	v_and_b32_e32 v11, 0xffff0000, v97
	v_pk_mul_f32 v[2:3], v[2:3], v[10:11]
	v_pk_add_f32 v[6:7], v[8:9], 1.0 op_sel_hi:[1,0]
	v_cvt_pk_bf16_f32 v0, v0, v1
	v_rcp_f32_e32 v9, v7
	s_nop 0
	v_mul_f32_e32 v8, v13, v9
	v_mov_b32_e32 v7, v8
	v_rcp_f32_e32 v9, v6
	s_nop 0
	v_mul_f32_e32 v8, v12, v9
	v_mov_b32_e32 v6, v8
	v_pk_mul_f32 v[2:3], v[6:7], v[2:3]
	s_nop 0
	v_cvt_pk_bf16_f32 v1, v2, v3
	global_store_dwordx2 v[4:5], v[0:1], off offset:1024
	s_barrier
	s_cbranch_scc0 .LBB0_825
	s_branch .LBB0_826
.Lsgu_fast:
	v_mov_b32_e32 v17, v174
	s_ashr_i32 s8, s65, 7
	v_mov_b32_e32 v130, v217
	s_ashr_i32 s9, s8, 31
	v_ashrrev_i32_e32 v0, 2, v130
	s_lshl_b64 s[36:37], s[8:9], 12
	s_and_b32 s7, s64, 0xf80
	v_add_u32_e32 v44, s10, v0
	s_or_b32 s36, s36, s7
	v_ashrrev_i32_e32 v45, 31, v44
	v_lshl_add_u64 v[0:1], s[36:37], 0, v[44:45]
	v_mov_b64_e32 v[2:3], s[82:83]
	v_mad_u64_u32 v[2:3], s[8:9], v0, s14, v[2:3]
	v_lshlrev_b32_e32 v0, 3, v130
	v_and_b32_e32 v45, 24, v0
	v_mad_i32_i24 v3, v1, s14, v3
	v_lshlrev_b32_e32 v194, 1, v45
	v_lshl_add_u64 v[0:1], v[2:3], 0, v[194:195]
	v_lshl_add_u64 v[2:3], v[0:1], 0, s[66:67]
	v_add_co_u32_e32 v0, vcc, s15, v0
	v_mov_b32_e32 v100, v195
	s_nop 0
	v_addc_co_u32_e32 v1, vcc, 0, v1, vcc
	s_and_b32 s45, s65, 3
	s_lshl_b32 s60, s45, 7
	s_lshl_b32 s92, s45, 8
	s_lshl_b32 s7, s45, 9
	s_add_u32 s40, s12, s7
	s_addc_u32 s41, s16, 0
	v_lshl_add_u64 v[0:1], v[2:3], 0, s[92:93]
	s_add_u32 s46, s17, s7
	global_load_dwordx4 v[12:15], v[0:1], off
	global_load_dwordx4 v[8:11], v[0:1], off offset:64
	global_load_dwordx4 v[4:7], v[0:1], off offset:128
	s_nop 0
	global_load_dwordx4 v[0:3], v[0:1], off offset:192
	s_addc_u32 s47, s18, 0
	s_add_u32 s8, s33, s92
	v_and_b32_e32 v132, 15, v130
	s_addc_u32 s9, s34, 0
	s_lshl_b32 s7, s45, 15
	v_lshlrev_b32_e32 v194, 8, v132
	v_and_b32_e32 v21, 64, v224
	v_xor_b32_e32 v20, 1, v224
	v_add_u32_e32 v21, 64, v21
	v_cmp_lt_i32_e32 vcc, v20, v21
	v_cndmask_b32_e32 v20, v224, v20, vcc
	v_lshlrev_b32_e32 v164, 2, v20
	v_xor_b32_e32 v20, 2, v224
	v_cmp_lt_i32_e32 vcc, v20, v21
	v_cndmask_b32_e32 v20, v224, v20, vcc
	v_lshlrev_b32_e32 v165, 2, v20
	s_nop 0
	s_nop 0
	s_waitcnt lgkmcnt(0)
	s_waitcnt lgkmcnt(0)
	v_mul_f32_e32 v16, 0x3b000000, v17
	v_lshlrev_b32_e32 v35, 2, v45
	s_waitcnt vmcnt(0)
	v_lshlrev_b32_e32 v36, 16, v12
	v_and_b32_e32 v12, 0xffff0000, v12
	v_fmac_f32_e32 v36, 0xbb000000, v17
	v_fmac_f32_e32 v12, 0xbb000000, v17
	v_lshlrev_b32_e32 v34, 1, v44
	v_lshlrev_b32_e32 v37, 16, v13
	v_fmac_f32_e32 v37, 0xbb000000, v17
	v_and_b32_e32 v13, 0xffff0000, v13
	s_waitcnt lgkmcnt(0)
	v_fmac_f32_e32 v13, 0xbb000000, v17
	v_lshlrev_b32_e32 v38, 16, v14
	v_fmac_f32_e32 v38, 0xbb000000, v17
	v_and_b32_e32 v14, 0xffff0000, v14
	s_waitcnt lgkmcnt(0)
	v_fmac_f32_e32 v14, 0xbb000000, v17
	v_lshlrev_b32_e32 v39, 16, v15
	v_fmac_f32_e32 v39, 0xbb000000, v17
	v_and_b32_e32 v15, 0xffff0000, v15
	v_mov_b32_e32 v16, v175
	s_branch .Lsgu_join
